# P1/P9 EpiScaleBf16 epilogues: the 8 row-scale loads issued up front instead of one per block with a full drain each
# speedup vs baseline: 1.0350x; 1.0350x over previous
.LBB0_277:
	v_lshl_add_u32 v144, s22, 8, v152
	v_ashrrev_i32_e32 v145, 31, v144
	v_lshl_add_u64 v[148:149], v[144:145], 2, s[6:7]
	global_load_dword v160, v[148:149], off
	global_load_dword v232, v[148:149], off offset:64
	global_load_dword v233, v[148:149], off offset:128
	global_load_dword v234, v[148:149], off offset:192
	global_load_dword v235, v[148:149], off offset:512
	global_load_dword v236, v[148:149], off offset:576
	global_load_dword v237, v[148:149], off offset:640
	global_load_dword v238, v[148:149], off offset:704
	v_lshl_or_b32 v150, s51, 8, v154
	v_mov_b64_e32 v[146:147], s[4:5]
	v_ashrrev_i32_e32 v151, 31, v150
	v_mad_i64_i32 v[162:163], s[24:25], v144, s50, v[146:147]
	v_or_b32_e32 v164, 16, v144
	v_lshlrev_b64 v[150:151], 1, v[150:151]
	v_ashrrev_i32_e32 v165, 31, v164
	v_lshl_add_u64 v[162:163], v[162:163], 0, v[150:151]
	v_lshl_add_u64 v[166:167], v[164:165], 2, s[6:7]
	s_andn2_b64 vcc, exec, s[0:1]
	s_mov_b64 s[0:1], -1
	s_waitcnt vmcnt(0)
	v_pk_mul_f32 v[126:127], v[126:127], v[160:161] op_sel_hi:[1,0]
	v_pk_mul_f32 v[124:125], v[124:125], v[160:161] op_sel_hi:[1,0]
	v_pk_mul_f32 v[122:123], v[122:123], v[160:161] op_sel_hi:[1,0]
	v_pk_mul_f32 v[120:121], v[120:121], v[160:161] op_sel_hi:[1,0]
	v_pk_mul_f32 v[118:119], v[118:119], v[160:161] op_sel_hi:[1,0]
	v_pk_mul_f32 v[116:117], v[116:117], v[160:161] op_sel_hi:[1,0]
	v_pk_mul_f32 v[168:169], v[114:115], v[160:161] op_sel_hi:[1,0]
	v_pk_mul_f32 v[160:161], v[112:113], v[160:161] op_sel_hi:[1,0]
	v_cvt_pk_bf16_f32 v112, v124, v125
	v_cvt_pk_bf16_f32 v113, v126, v127
	v_cvt_pk_bf16_f32 v114, v120, v121
	v_cvt_pk_bf16_f32 v115, v122, v123
	global_store_dwordx4 v[162:163], v[112:115], off
	s_nop 1
	v_cvt_pk_bf16_f32 v112, v116, v117
	v_cvt_pk_bf16_f32 v113, v118, v119
	v_cvt_pk_bf16_f32 v114, v160, v161
	v_cvt_pk_bf16_f32 v115, v168, v169
	global_store_dwordx4 v[162:163], v[112:115], off offset:256
	s_nop 1
	v_mad_i64_i32 v[116:117], s[24:25], v164, s50, v[146:147]
	v_or_b32_e32 v114, 32, v144
	v_ashrrev_i32_e32 v115, 31, v114
	v_lshl_add_u64 v[116:117], v[116:117], 0, v[150:151]
	v_lshl_add_u64 v[118:119], v[114:115], 2, s[6:7]
	v_mov_b32_e32 v112, v232
	v_pk_mul_f32 v[110:111], v[110:111], v[112:113] op_sel_hi:[1,0]
	v_pk_mul_f32 v[108:109], v[108:109], v[112:113] op_sel_hi:[1,0]
	v_pk_mul_f32 v[106:107], v[106:107], v[112:113] op_sel_hi:[1,0]
	v_pk_mul_f32 v[104:105], v[104:105], v[112:113] op_sel_hi:[1,0]
	v_pk_mul_f32 v[102:103], v[102:103], v[112:113] op_sel_hi:[1,0]
	v_pk_mul_f32 v[100:101], v[100:101], v[112:113] op_sel_hi:[1,0]
	v_pk_mul_f32 v[120:121], v[98:99], v[112:113] op_sel_hi:[1,0]
	v_pk_mul_f32 v[112:113], v[96:97], v[112:113] op_sel_hi:[1,0]
	v_cvt_pk_bf16_f32 v96, v108, v109
	v_cvt_pk_bf16_f32 v97, v110, v111
	v_cvt_pk_bf16_f32 v98, v104, v105
	v_cvt_pk_bf16_f32 v99, v106, v107
	global_store_dwordx4 v[116:117], v[96:99], off
	s_nop 1
	v_cvt_pk_bf16_f32 v96, v100, v101
	v_cvt_pk_bf16_f32 v97, v102, v103
	v_cvt_pk_bf16_f32 v98, v112, v113
	v_cvt_pk_bf16_f32 v99, v120, v121
	global_store_dwordx4 v[116:117], v[96:99], off offset:256
	s_nop 1
	v_mad_i64_i32 v[100:101], s[24:25], v114, s50, v[146:147]
	v_or_b32_e32 v98, 48, v144
	v_ashrrev_i32_e32 v99, 31, v98
	v_lshl_add_u64 v[100:101], v[100:101], 0, v[150:151]
	v_lshl_add_u64 v[102:103], v[98:99], 2, s[6:7]
	v_mov_b32_e32 v96, v233
	v_pk_mul_f32 v[94:95], v[94:95], v[96:97] op_sel_hi:[1,0]
	v_pk_mul_f32 v[92:93], v[92:93], v[96:97] op_sel_hi:[1,0]
	v_pk_mul_f32 v[90:91], v[90:91], v[96:97] op_sel_hi:[1,0]
	v_pk_mul_f32 v[88:89], v[88:89], v[96:97] op_sel_hi:[1,0]
	v_pk_mul_f32 v[82:83], v[82:83], v[96:97] op_sel_hi:[1,0]
	v_pk_mul_f32 v[80:81], v[80:81], v[96:97] op_sel_hi:[1,0]
	v_pk_mul_f32 v[104:105], v[74:75], v[96:97] op_sel_hi:[1,0]
	v_pk_mul_f32 v[96:97], v[72:73], v[96:97] op_sel_hi:[1,0]
	v_cvt_pk_bf16_f32 v72, v92, v93
	v_cvt_pk_bf16_f32 v73, v94, v95
	v_cvt_pk_bf16_f32 v74, v88, v89
	v_cvt_pk_bf16_f32 v75, v90, v91
	global_store_dwordx4 v[100:101], v[72:75], off
	s_nop 1
	v_cvt_pk_bf16_f32 v72, v80, v81
	v_cvt_pk_bf16_f32 v73, v82, v83
	v_cvt_pk_bf16_f32 v74, v96, v97
	v_cvt_pk_bf16_f32 v75, v104, v105
	global_store_dwordx4 v[100:101], v[72:75], off offset:256
	s_nop 1
	v_mov_b32_e32 v72, v234
	v_pk_mul_f32 v[80:81], v[86:87], v[72:73] op_sel_hi:[1,0]
	v_mad_i64_i32 v[74:75], s[24:25], v98, s50, v[146:147]
	v_lshl_add_u64 v[74:75], v[74:75], 0, v[150:151]
	v_pk_mul_f32 v[82:83], v[84:85], v[72:73] op_sel_hi:[1,0]
	v_pk_mul_f32 v[78:79], v[78:79], v[72:73] op_sel_hi:[1,0]
	v_pk_mul_f32 v[76:77], v[76:77], v[72:73] op_sel_hi:[1,0]
	v_pk_mul_f32 v[70:71], v[70:71], v[72:73] op_sel_hi:[1,0]
	v_pk_mul_f32 v[68:69], v[68:69], v[72:73] op_sel_hi:[1,0]
	v_pk_mul_f32 v[84:85], v[66:67], v[72:73] op_sel_hi:[1,0]
	v_pk_mul_f32 v[72:73], v[64:65], v[72:73] op_sel_hi:[1,0]
	v_cvt_pk_bf16_f32 v64, v82, v83
	v_cvt_pk_bf16_f32 v65, v80, v81
	v_cvt_pk_bf16_f32 v66, v76, v77
	v_cvt_pk_bf16_f32 v67, v78, v79
	global_store_dwordx4 v[74:75], v[64:67], off
	s_nop 1
	v_cvt_pk_bf16_f32 v64, v68, v69
	v_cvt_pk_bf16_f32 v65, v70, v71
	v_cvt_pk_bf16_f32 v66, v72, v73
	v_cvt_pk_bf16_f32 v67, v84, v85
	global_store_dwordx4 v[74:75], v[64:67], off offset:256
	s_nop 1
	s_nop 0
	v_add_u32_e32 v65, 0x80, v144
	v_mad_i64_i32 v[66:67], s[24:25], v65, s50, v[146:147]
	v_lshl_add_u64 v[66:67], v[66:67], 0, v[150:151]
	v_mov_b32_e32 v64, v235
	v_pk_mul_f32 v[62:63], v[62:63], v[64:65] op_sel_hi:[1,0]
	v_pk_mul_f32 v[60:61], v[60:61], v[64:65] op_sel_hi:[1,0]
	v_pk_mul_f32 v[58:59], v[58:59], v[64:65] op_sel_hi:[1,0]
	v_pk_mul_f32 v[56:57], v[56:57], v[64:65] op_sel_hi:[1,0]
	v_pk_mul_f32 v[54:55], v[54:55], v[64:65] op_sel_hi:[1,0]
	v_pk_mul_f32 v[52:53], v[52:53], v[64:65] op_sel_hi:[1,0]
	v_pk_mul_f32 v[68:69], v[50:51], v[64:65] op_sel_hi:[1,0]
	v_pk_mul_f32 v[64:65], v[48:49], v[64:65] op_sel_hi:[1,0]
	v_cvt_pk_bf16_f32 v48, v60, v61
	v_cvt_pk_bf16_f32 v49, v62, v63
	v_cvt_pk_bf16_f32 v50, v56, v57
	v_cvt_pk_bf16_f32 v51, v58, v59
	global_store_dwordx4 v[66:67], v[48:51], off
	s_nop 1
	v_cvt_pk_bf16_f32 v48, v52, v53
	v_cvt_pk_bf16_f32 v49, v54, v55
	v_cvt_pk_bf16_f32 v50, v64, v65
	v_cvt_pk_bf16_f32 v51, v68, v69
	global_store_dwordx4 v[66:67], v[48:51], off offset:256
	s_nop 1
	s_nop 0
	v_add_u32_e32 v49, 0x90, v144
	v_mad_i64_i32 v[50:51], s[24:25], v49, s50, v[146:147]
	v_lshl_add_u64 v[50:51], v[50:51], 0, v[150:151]
	v_mov_b32_e32 v48, v236
	v_pk_mul_f32 v[46:47], v[46:47], v[48:49] op_sel_hi:[1,0]
	v_pk_mul_f32 v[44:45], v[44:45], v[48:49] op_sel_hi:[1,0]
	v_pk_mul_f32 v[42:43], v[42:43], v[48:49] op_sel_hi:[1,0]
	v_pk_mul_f32 v[40:41], v[40:41], v[48:49] op_sel_hi:[1,0]
	v_pk_mul_f32 v[38:39], v[38:39], v[48:49] op_sel_hi:[1,0]
	v_pk_mul_f32 v[36:37], v[36:37], v[48:49] op_sel_hi:[1,0]
	v_pk_mul_f32 v[52:53], v[34:35], v[48:49] op_sel_hi:[1,0]
	v_pk_mul_f32 v[48:49], v[32:33], v[48:49] op_sel_hi:[1,0]
	v_cvt_pk_bf16_f32 v32, v44, v45
	v_cvt_pk_bf16_f32 v33, v46, v47
	v_cvt_pk_bf16_f32 v34, v40, v41
	v_cvt_pk_bf16_f32 v35, v42, v43
	global_store_dwordx4 v[50:51], v[32:35], off
	s_nop 1
	v_cvt_pk_bf16_f32 v32, v36, v37
	v_cvt_pk_bf16_f32 v33, v38, v39
	v_cvt_pk_bf16_f32 v34, v48, v49
	v_cvt_pk_bf16_f32 v35, v52, v53
	global_store_dwordx4 v[50:51], v[32:35], off offset:256
	s_nop 1
	s_nop 0
	v_add_u32_e32 v33, 0xa0, v144
	v_mad_i64_i32 v[34:35], s[24:25], v33, s50, v[146:147]
	v_lshl_add_u64 v[34:35], v[34:35], 0, v[150:151]
	v_mov_b32_e32 v32, v237
	v_pk_mul_f32 v[30:31], v[30:31], v[32:33] op_sel_hi:[1,0]
	v_pk_mul_f32 v[28:29], v[28:29], v[32:33] op_sel_hi:[1,0]
	v_pk_mul_f32 v[26:27], v[26:27], v[32:33] op_sel_hi:[1,0]
	v_pk_mul_f32 v[24:25], v[24:25], v[32:33] op_sel_hi:[1,0]
	v_pk_mul_f32 v[22:23], v[22:23], v[32:33] op_sel_hi:[1,0]
	v_pk_mul_f32 v[20:21], v[20:21], v[32:33] op_sel_hi:[1,0]
	v_pk_mul_f32 v[36:37], v[18:19], v[32:33] op_sel_hi:[1,0]
	v_pk_mul_f32 v[32:33], v[16:17], v[32:33] op_sel_hi:[1,0]
	v_cvt_pk_bf16_f32 v16, v28, v29
	v_cvt_pk_bf16_f32 v17, v30, v31
	v_cvt_pk_bf16_f32 v18, v24, v25
	v_cvt_pk_bf16_f32 v19, v26, v27
	global_store_dwordx4 v[34:35], v[16:19], off
	s_nop 1
	v_cvt_pk_bf16_f32 v16, v20, v21
	v_cvt_pk_bf16_f32 v17, v22, v23
	v_cvt_pk_bf16_f32 v18, v32, v33
	v_cvt_pk_bf16_f32 v19, v36, v37
	global_store_dwordx4 v[34:35], v[16:19], off offset:256
	s_nop 1
	s_nop 0
	v_add_u32_e32 v17, 0xb0, v144
	v_mad_i64_i32 v[18:19], s[24:25], v17, s50, v[146:147]
	v_lshl_add_u64 v[18:19], v[18:19], 0, v[150:151]
	v_mov_b32_e32 v16, v238
	v_pk_mul_f32 v[14:15], v[14:15], v[16:17] op_sel_hi:[1,0]
	v_pk_mul_f32 v[12:13], v[12:13], v[16:17] op_sel_hi:[1,0]
	v_pk_mul_f32 v[10:11], v[10:11], v[16:17] op_sel_hi:[1,0]
	v_pk_mul_f32 v[8:9], v[8:9], v[16:17] op_sel_hi:[1,0]
	v_pk_mul_f32 v[6:7], v[6:7], v[16:17] op_sel_hi:[1,0]
	v_pk_mul_f32 v[4:5], v[4:5], v[16:17] op_sel_hi:[1,0]
	v_pk_mul_f32 v[20:21], v[2:3], v[16:17] op_sel_hi:[1,0]
	v_pk_mul_f32 v[16:17], v[0:1], v[16:17] op_sel_hi:[1,0]
	v_cvt_pk_bf16_f32 v0, v12, v13
	v_cvt_pk_bf16_f32 v1, v14, v15
	v_cvt_pk_bf16_f32 v2, v8, v9
	v_cvt_pk_bf16_f32 v3, v10, v11
	global_store_dwordx4 v[18:19], v[0:3], off
	s_nop 1
	v_cvt_pk_bf16_f32 v0, v4, v5
	v_cvt_pk_bf16_f32 v1, v6, v7
	v_cvt_pk_bf16_f32 v2, v16, v17
	v_cvt_pk_bf16_f32 v3, v20, v21
	global_store_dwordx4 v[18:19], v[0:3], off offset:256
	s_cbranch_vccnz .LBB0_270
	s_andn2_b64 vcc, exec, s[2:3]
	s_cbranch_vccnz .LBB0_269
	s_barrier
	s_branch .LBB0_269

.LBB0_1429:
	v_lshl_add_u32 v148, s2, 8, v152
	v_ashrrev_i32_e32 v149, 31, v148
	v_lshl_add_u64 v[144:145], v[148:149], 2, s[8:9]
	global_load_dword v164, v[144:145], off
	global_load_dword v232, v[144:145], off offset:64
	global_load_dword v233, v[144:145], off offset:128
	global_load_dword v234, v[144:145], off offset:192
	global_load_dword v235, v[144:145], off offset:512
	global_load_dword v236, v[144:145], off offset:576
	global_load_dword v237, v[144:145], off offset:640
	global_load_dword v238, v[144:145], off offset:704
	v_lshl_or_b32 v146, s3, 8, v154
	v_ashrrev_i32_e32 v147, 31, v146
	v_lshlrev_b64 v[150:151], 1, v[146:147]
	v_lshlrev_b64 v[162:163], 14, v[148:149]
	v_or_b32_e32 v160, 16, v148
	v_ashrrev_i32_e32 v161, 31, v160
	s_waitcnt vmcnt(0)
	v_fmamk_f32 v146, v164, 0x3a000000, v159
	v_mul_f32_e32 v147, 0x4b800000, v146
	v_cmp_gt_f32_e32 vcc, s56, v146
	s_nop 1
	v_cndmask_b32_e32 v146, v146, v147, vcc
	v_rsq_f32_e32 v149, v146
	v_lshl_add_u64 v[146:147], s[6:7], 0, v[162:163]
	v_lshl_add_u64 v[146:147], v[146:147], 0, v[150:151]
	v_lshl_add_u64 v[162:163], v[160:161], 2, s[8:9]
	v_mul_f32_e32 v164, 0x45800000, v149
	v_cndmask_b32_e32 v164, v149, v164, vcc
	v_pk_mul_f32 v[126:127], v[126:127], v[164:165] op_sel_hi:[1,0]
	v_pk_mul_f32 v[124:125], v[124:125], v[164:165] op_sel_hi:[1,0]
	v_pk_mul_f32 v[122:123], v[122:123], v[164:165] op_sel_hi:[1,0]
	v_pk_mul_f32 v[120:121], v[120:121], v[164:165] op_sel_hi:[1,0]
	v_pk_mul_f32 v[114:115], v[114:115], v[164:165] op_sel_hi:[1,0]
	v_pk_mul_f32 v[112:113], v[112:113], v[164:165] op_sel_hi:[1,0]
	v_pk_mul_f32 v[118:119], v[118:119], v[164:165] op_sel_hi:[1,0]
	v_pk_mul_f32 v[116:117], v[116:117], v[164:165] op_sel_hi:[1,0]
	v_max_f32_e32 v124, 0, v124
	v_max_f32_e32 v120, 0, v120
	v_max_f32_e32 v125, 0, v125
	v_max_f32_e32 v121, 0, v121
	v_max_f32_e32 v126, 0, v126
	v_max_f32_e32 v122, 0, v122
	v_max_f32_e32 v127, 0, v127
	v_max_f32_e32 v123, 0, v123
	v_max_f32_e32 v112, 0, v112
	v_max_f32_e32 v113, 0, v113
	v_max_f32_e32 v114, 0, v114
	v_max_f32_e32 v115, 0, v115
	v_max_f32_e32 v116, 0, v116
	v_max_f32_e32 v117, 0, v117
	v_max_f32_e32 v118, 0, v118
	v_max_f32_e32 v119, 0, v119
	v_mul_f32_e32 v124, v124, v124
	v_mul_f32_e32 v120, v120, v120
	v_mul_f32_e32 v125, v125, v125
	v_mul_f32_e32 v121, v121, v121
	v_mul_f32_e32 v126, v126, v126
	v_mul_f32_e32 v122, v122, v122
	v_mul_f32_e32 v127, v127, v127
	v_mul_f32_e32 v123, v123, v123
	v_mul_f32_e32 v149, v112, v112
	v_mul_f32_e32 v164, v113, v113
	v_mul_f32_e32 v165, v114, v114
	v_mul_f32_e32 v166, v115, v115
	v_cvt_pk_bf16_f32 v112, v124, v125
	v_cvt_pk_bf16_f32 v113, v126, v127
	v_cvt_pk_bf16_f32 v114, v120, v121
	v_cvt_pk_bf16_f32 v115, v122, v123
	v_mul_f32_e32 v116, v116, v116
	v_mul_f32_e32 v117, v117, v117
	v_mul_f32_e32 v118, v118, v118
	v_mul_f32_e32 v119, v119, v119
	global_store_dwordx4 v[146:147], v[112:115], off
	s_nop 1
	v_cvt_pk_bf16_f32 v112, v116, v117
	v_cvt_pk_bf16_f32 v113, v118, v119
	v_cvt_pk_bf16_f32 v114, v149, v164
	v_cvt_pk_bf16_f32 v115, v165, v166
	global_store_dwordx4 v[146:147], v[112:115], off offset:256
	s_nop 1
	v_mov_b32_e32 v116, v232
	v_fmamk_f32 v116, v116, 0x3a000000, v159
	v_mul_f32_e32 v117, 0x4b800000, v116
	v_cmp_gt_f32_e32 vcc, s56, v116
	v_lshlrev_b64 v[114:115], 14, v[160:161]
	v_or_b32_e32 v112, 32, v148
	v_cndmask_b32_e32 v116, v116, v117, vcc
	v_rsq_f32_e32 v118, v116
	v_lshl_add_u64 v[114:115], s[6:7], 0, v[114:115]
	v_ashrrev_i32_e32 v113, 31, v112
	v_lshl_add_u64 v[114:115], v[114:115], 0, v[150:151]
	v_mul_f32_e32 v119, 0x45800000, v118
	v_cndmask_b32_e32 v118, v118, v119, vcc
	v_pk_mul_f32 v[110:111], v[110:111], v[118:119] op_sel_hi:[1,0]
	v_pk_mul_f32 v[108:109], v[108:109], v[118:119] op_sel_hi:[1,0]
	v_pk_mul_f32 v[106:107], v[106:107], v[118:119] op_sel_hi:[1,0]
	v_pk_mul_f32 v[104:105], v[104:105], v[118:119] op_sel_hi:[1,0]
	v_pk_mul_f32 v[98:99], v[98:99], v[118:119] op_sel_hi:[1,0]
	v_pk_mul_f32 v[96:97], v[96:97], v[118:119] op_sel_hi:[1,0]
	v_pk_mul_f32 v[102:103], v[102:103], v[118:119] op_sel_hi:[1,0]
	v_pk_mul_f32 v[100:101], v[100:101], v[118:119] op_sel_hi:[1,0]
	v_max_f32_e32 v108, 0, v108
	v_max_f32_e32 v104, 0, v104
	v_max_f32_e32 v109, 0, v109
	v_max_f32_e32 v105, 0, v105
	v_max_f32_e32 v110, 0, v110
	v_max_f32_e32 v106, 0, v106
	v_max_f32_e32 v111, 0, v111
	v_max_f32_e32 v107, 0, v107
	v_max_f32_e32 v96, 0, v96
	v_max_f32_e32 v97, 0, v97
	v_max_f32_e32 v98, 0, v98
	v_max_f32_e32 v99, 0, v99
	v_max_f32_e32 v100, 0, v100
	v_max_f32_e32 v101, 0, v101
	v_max_f32_e32 v102, 0, v102
	v_max_f32_e32 v103, 0, v103
	v_mul_f32_e32 v108, v108, v108
	v_mul_f32_e32 v104, v104, v104
	v_mul_f32_e32 v109, v109, v109
	v_mul_f32_e32 v105, v105, v105
	v_mul_f32_e32 v110, v110, v110
	v_mul_f32_e32 v106, v106, v106
	v_mul_f32_e32 v111, v111, v111
	v_mul_f32_e32 v107, v107, v107
	v_mul_f32_e32 v118, v96, v96
	v_mul_f32_e32 v119, v97, v97
	v_mul_f32_e32 v120, v98, v98
	v_mul_f32_e32 v121, v99, v99
	v_cvt_pk_bf16_f32 v96, v108, v109
	v_cvt_pk_bf16_f32 v97, v110, v111
	v_cvt_pk_bf16_f32 v98, v104, v105
	v_cvt_pk_bf16_f32 v99, v106, v107
	v_lshl_add_u64 v[116:117], v[112:113], 2, s[8:9]
	v_mul_f32_e32 v100, v100, v100
	v_mul_f32_e32 v101, v101, v101
	v_mul_f32_e32 v102, v102, v102
	v_mul_f32_e32 v103, v103, v103
	global_store_dwordx4 v[114:115], v[96:99], off
	s_nop 1
	v_cvt_pk_bf16_f32 v96, v100, v101
	v_cvt_pk_bf16_f32 v97, v102, v103
	v_cvt_pk_bf16_f32 v98, v118, v119
	v_cvt_pk_bf16_f32 v99, v120, v121
	global_store_dwordx4 v[114:115], v[96:99], off offset:256
	s_nop 1
	v_mov_b32_e32 v100, v233
	v_fmamk_f32 v100, v100, 0x3a000000, v159
	v_mul_f32_e32 v101, 0x4b800000, v100
	v_cmp_gt_f32_e32 vcc, s56, v100
	v_lshlrev_b64 v[98:99], 14, v[112:113]
	v_or_b32_e32 v96, 48, v148
	v_cndmask_b32_e32 v100, v100, v101, vcc
	v_rsq_f32_e32 v102, v100
	v_lshl_add_u64 v[98:99], s[6:7], 0, v[98:99]
	v_ashrrev_i32_e32 v97, 31, v96
	v_lshl_add_u64 v[98:99], v[98:99], 0, v[150:151]
	v_mul_f32_e32 v103, 0x45800000, v102
	v_cndmask_b32_e32 v102, v102, v103, vcc
	v_pk_mul_f32 v[94:95], v[94:95], v[102:103] op_sel_hi:[1,0]
	v_pk_mul_f32 v[92:93], v[92:93], v[102:103] op_sel_hi:[1,0]
	v_pk_mul_f32 v[90:91], v[90:91], v[102:103] op_sel_hi:[1,0]
	v_pk_mul_f32 v[88:89], v[88:89], v[102:103] op_sel_hi:[1,0]
	v_pk_mul_f32 v[82:83], v[82:83], v[102:103] op_sel_hi:[1,0]
	v_pk_mul_f32 v[80:81], v[80:81], v[102:103] op_sel_hi:[1,0]
	v_pk_mul_f32 v[86:87], v[86:87], v[102:103] op_sel_hi:[1,0]
	v_pk_mul_f32 v[84:85], v[84:85], v[102:103] op_sel_hi:[1,0]
	v_max_f32_e32 v92, 0, v92
	v_max_f32_e32 v88, 0, v88
	v_max_f32_e32 v93, 0, v93
	v_max_f32_e32 v89, 0, v89
	v_max_f32_e32 v94, 0, v94
	v_max_f32_e32 v90, 0, v90
	v_max_f32_e32 v95, 0, v95
	v_max_f32_e32 v91, 0, v91
	v_max_f32_e32 v80, 0, v80
	v_max_f32_e32 v81, 0, v81
	v_max_f32_e32 v82, 0, v82
	v_max_f32_e32 v83, 0, v83
	v_max_f32_e32 v84, 0, v84
	v_max_f32_e32 v85, 0, v85
	v_max_f32_e32 v86, 0, v86
	v_max_f32_e32 v87, 0, v87
	v_mul_f32_e32 v92, v92, v92
	v_mul_f32_e32 v88, v88, v88
	v_mul_f32_e32 v93, v93, v93
	v_mul_f32_e32 v89, v89, v89
	v_mul_f32_e32 v94, v94, v94
	v_mul_f32_e32 v90, v90, v90
	v_mul_f32_e32 v95, v95, v95
	v_mul_f32_e32 v91, v91, v91
	v_mul_f32_e32 v102, v80, v80
	v_mul_f32_e32 v103, v81, v81
	v_mul_f32_e32 v104, v82, v82
	v_mul_f32_e32 v105, v83, v83
	v_cvt_pk_bf16_f32 v80, v92, v93
	v_cvt_pk_bf16_f32 v81, v94, v95
	v_cvt_pk_bf16_f32 v82, v88, v89
	v_cvt_pk_bf16_f32 v83, v90, v91
	v_lshl_add_u64 v[100:101], v[96:97], 2, s[8:9]
	v_mul_f32_e32 v84, v84, v84
	v_mul_f32_e32 v85, v85, v85
	v_mul_f32_e32 v86, v86, v86
	v_mul_f32_e32 v87, v87, v87
	global_store_dwordx4 v[98:99], v[80:83], off
	s_nop 1
	v_cvt_pk_bf16_f32 v80, v84, v85
	v_cvt_pk_bf16_f32 v81, v86, v87
	v_cvt_pk_bf16_f32 v82, v102, v103
	v_cvt_pk_bf16_f32 v83, v104, v105
	global_store_dwordx4 v[98:99], v[80:83], off offset:256
	s_nop 1
	v_mov_b32_e32 v80, v234
	v_fmamk_f32 v80, v80, 0x3a000000, v159
	v_mul_f32_e32 v81, 0x4b800000, v80
	v_cmp_gt_f32_e32 vcc, s56, v80
	s_nop 1
	v_cndmask_b32_e32 v80, v80, v81, vcc
	v_rsq_f32_e32 v82, v80
	v_lshlrev_b64 v[80:81], 14, v[96:97]
	v_lshl_add_u64 v[80:81], s[6:7], 0, v[80:81]
	v_lshl_add_u64 v[80:81], v[80:81], 0, v[150:151]
	v_mul_f32_e32 v83, 0x45800000, v82
	v_cndmask_b32_e32 v82, v82, v83, vcc
	v_pk_mul_f32 v[78:79], v[78:79], v[82:83] op_sel_hi:[1,0]
	v_pk_mul_f32 v[76:77], v[76:77], v[82:83] op_sel_hi:[1,0]
	v_pk_mul_f32 v[74:75], v[74:75], v[82:83] op_sel_hi:[1,0]
	v_pk_mul_f32 v[72:73], v[72:73], v[82:83] op_sel_hi:[1,0]
	v_pk_mul_f32 v[66:67], v[66:67], v[82:83] op_sel_hi:[1,0]
	v_pk_mul_f32 v[64:65], v[64:65], v[82:83] op_sel_hi:[1,0]
	v_pk_mul_f32 v[70:71], v[70:71], v[82:83] op_sel_hi:[1,0]
	v_pk_mul_f32 v[68:69], v[68:69], v[82:83] op_sel_hi:[1,0]
	v_max_f32_e32 v76, 0, v76
	v_max_f32_e32 v72, 0, v72
	v_max_f32_e32 v77, 0, v77
	v_max_f32_e32 v73, 0, v73
	v_max_f32_e32 v78, 0, v78
	v_max_f32_e32 v74, 0, v74
	v_max_f32_e32 v79, 0, v79
	v_max_f32_e32 v75, 0, v75
	v_max_f32_e32 v64, 0, v64
	v_max_f32_e32 v65, 0, v65
	v_max_f32_e32 v66, 0, v66
	v_max_f32_e32 v67, 0, v67
	v_max_f32_e32 v68, 0, v68
	v_max_f32_e32 v69, 0, v69
	v_max_f32_e32 v70, 0, v70
	v_max_f32_e32 v71, 0, v71
	v_mul_f32_e32 v76, v76, v76
	v_mul_f32_e32 v72, v72, v72
	v_mul_f32_e32 v77, v77, v77
	v_mul_f32_e32 v73, v73, v73
	v_mul_f32_e32 v78, v78, v78
	v_mul_f32_e32 v74, v74, v74
	v_mul_f32_e32 v79, v79, v79
	v_mul_f32_e32 v75, v75, v75
	v_mul_f32_e32 v82, v64, v64
	v_mul_f32_e32 v83, v65, v65
	v_mul_f32_e32 v84, v66, v66
	v_mul_f32_e32 v85, v67, v67
	v_cvt_pk_bf16_f32 v64, v76, v77
	v_cvt_pk_bf16_f32 v65, v78, v79
	v_cvt_pk_bf16_f32 v66, v72, v73
	v_cvt_pk_bf16_f32 v67, v74, v75
	v_mul_f32_e32 v68, v68, v68
	v_mul_f32_e32 v69, v69, v69
	v_mul_f32_e32 v70, v70, v70
	v_mul_f32_e32 v71, v71, v71
	global_store_dwordx4 v[80:81], v[64:67], off
	s_nop 1
	v_cvt_pk_bf16_f32 v64, v68, v69
	v_cvt_pk_bf16_f32 v65, v70, v71
	v_cvt_pk_bf16_f32 v66, v82, v83
	v_cvt_pk_bf16_f32 v67, v84, v85
	global_store_dwordx4 v[80:81], v[64:67], off offset:256
	s_nop 1
	s_nop 0
	v_lshl_add_u64 v[64:65], v[146:147], 0, s[14:15]
	v_mov_b32_e32 v66, v235
	v_fmamk_f32 v66, v66, 0x3a000000, v159
	v_mul_f32_e32 v67, 0x4b800000, v66
	v_cmp_gt_f32_e32 vcc, s56, v66
	s_nop 1
	v_cndmask_b32_e32 v66, v66, v67, vcc
	v_rsq_f32_e32 v68, v66
	v_add_co_u32_e64 v66, s[2:3], s57, v146
	v_mul_f32_e32 v69, 0x45800000, v68
	v_cndmask_b32_e32 v68, v68, v69, vcc
	v_pk_mul_f32 v[62:63], v[62:63], v[68:69] op_sel_hi:[1,0]
	v_pk_mul_f32 v[60:61], v[60:61], v[68:69] op_sel_hi:[1,0]
	v_pk_mul_f32 v[58:59], v[58:59], v[68:69] op_sel_hi:[1,0]
	v_pk_mul_f32 v[56:57], v[56:57], v[68:69] op_sel_hi:[1,0]
	v_pk_mul_f32 v[50:51], v[50:51], v[68:69] op_sel_hi:[1,0]
	v_pk_mul_f32 v[48:49], v[48:49], v[68:69] op_sel_hi:[1,0]
	v_pk_mul_f32 v[54:55], v[54:55], v[68:69] op_sel_hi:[1,0]
	v_pk_mul_f32 v[52:53], v[52:53], v[68:69] op_sel_hi:[1,0]
	v_max_f32_e32 v60, 0, v60
	v_max_f32_e32 v56, 0, v56
	v_max_f32_e32 v61, 0, v61
	v_max_f32_e32 v57, 0, v57
	v_max_f32_e32 v62, 0, v62
	v_max_f32_e32 v58, 0, v58
	v_max_f32_e32 v63, 0, v63
	v_max_f32_e32 v59, 0, v59
	v_max_f32_e32 v48, 0, v48
	v_max_f32_e32 v49, 0, v49
	v_max_f32_e32 v50, 0, v50
	v_max_f32_e32 v51, 0, v51
	v_addc_co_u32_e64 v67, s[2:3], 0, v147, s[2:3]
	v_max_f32_e32 v52, 0, v52
	v_max_f32_e32 v53, 0, v53
	v_max_f32_e32 v54, 0, v54
	v_max_f32_e32 v55, 0, v55
	v_mul_f32_e32 v60, v60, v60
	v_mul_f32_e32 v56, v56, v56
	v_mul_f32_e32 v61, v61, v61
	v_mul_f32_e32 v57, v57, v57
	v_mul_f32_e32 v62, v62, v62
	v_mul_f32_e32 v58, v58, v58
	v_mul_f32_e32 v63, v63, v63
	v_mul_f32_e32 v59, v59, v59
	v_mul_f32_e32 v68, v48, v48
	v_mul_f32_e32 v69, v49, v49
	v_mul_f32_e32 v70, v50, v50
	v_mul_f32_e32 v71, v51, v51
	v_cvt_pk_bf16_f32 v48, v60, v61
	v_cvt_pk_bf16_f32 v49, v62, v63
	v_cvt_pk_bf16_f32 v50, v56, v57
	v_cvt_pk_bf16_f32 v51, v58, v59
	v_mul_f32_e32 v52, v52, v52
	v_mul_f32_e32 v53, v53, v53
	v_mul_f32_e32 v54, v54, v54
	v_mul_f32_e32 v55, v55, v55
	global_store_dwordx4 v[66:67], v[48:51], off
	s_nop 1
	v_cvt_pk_bf16_f32 v48, v52, v53
	v_cvt_pk_bf16_f32 v49, v54, v55
	v_cvt_pk_bf16_f32 v50, v68, v69
	v_cvt_pk_bf16_f32 v51, v70, v71
	global_store_dwordx4 v[64:65], v[48:51], off offset:256
	s_nop 1
	s_nop 0
	v_lshl_add_u64 v[48:49], v[146:147], 0, s[16:17]
	v_mov_b32_e32 v50, v236
	v_fmamk_f32 v50, v50, 0x3a000000, v159
	v_mul_f32_e32 v51, 0x4b800000, v50
	v_cmp_gt_f32_e32 vcc, s56, v50
	s_nop 1
	v_cndmask_b32_e32 v50, v50, v51, vcc
	v_rsq_f32_e32 v52, v50
	v_add_co_u32_e64 v50, s[2:3], s58, v146
	v_mul_f32_e32 v53, 0x45800000, v52
	v_cndmask_b32_e32 v52, v52, v53, vcc
	v_pk_mul_f32 v[46:47], v[46:47], v[52:53] op_sel_hi:[1,0]
	v_pk_mul_f32 v[44:45], v[44:45], v[52:53] op_sel_hi:[1,0]
	v_pk_mul_f32 v[42:43], v[42:43], v[52:53] op_sel_hi:[1,0]
	v_pk_mul_f32 v[40:41], v[40:41], v[52:53] op_sel_hi:[1,0]
	v_pk_mul_f32 v[34:35], v[34:35], v[52:53] op_sel_hi:[1,0]
	v_pk_mul_f32 v[32:33], v[32:33], v[52:53] op_sel_hi:[1,0]
	v_pk_mul_f32 v[38:39], v[38:39], v[52:53] op_sel_hi:[1,0]
	v_pk_mul_f32 v[36:37], v[36:37], v[52:53] op_sel_hi:[1,0]
	v_max_f32_e32 v44, 0, v44
	v_max_f32_e32 v40, 0, v40
	v_max_f32_e32 v45, 0, v45
	v_max_f32_e32 v41, 0, v41
	v_max_f32_e32 v46, 0, v46
	v_max_f32_e32 v42, 0, v42
	v_max_f32_e32 v47, 0, v47
	v_max_f32_e32 v43, 0, v43
	v_max_f32_e32 v32, 0, v32
	v_max_f32_e32 v33, 0, v33
	v_max_f32_e32 v34, 0, v34
	v_max_f32_e32 v35, 0, v35
	v_addc_co_u32_e64 v51, s[2:3], 0, v147, s[2:3]
	v_max_f32_e32 v36, 0, v36
	v_max_f32_e32 v37, 0, v37
	v_max_f32_e32 v38, 0, v38
	v_max_f32_e32 v39, 0, v39
	v_mul_f32_e32 v44, v44, v44
	v_mul_f32_e32 v40, v40, v40
	v_mul_f32_e32 v45, v45, v45
	v_mul_f32_e32 v41, v41, v41
	v_mul_f32_e32 v46, v46, v46
	v_mul_f32_e32 v42, v42, v42
	v_mul_f32_e32 v47, v47, v47
	v_mul_f32_e32 v43, v43, v43
	v_mul_f32_e32 v52, v32, v32
	v_mul_f32_e32 v53, v33, v33
	v_mul_f32_e32 v54, v34, v34
	v_mul_f32_e32 v55, v35, v35
	v_cvt_pk_bf16_f32 v32, v44, v45
	v_cvt_pk_bf16_f32 v33, v46, v47
	v_cvt_pk_bf16_f32 v34, v40, v41
	v_cvt_pk_bf16_f32 v35, v42, v43
	v_mul_f32_e32 v36, v36, v36
	v_mul_f32_e32 v37, v37, v37
	v_mul_f32_e32 v38, v38, v38
	v_mul_f32_e32 v39, v39, v39
	global_store_dwordx4 v[50:51], v[32:35], off
	s_nop 1
	v_cvt_pk_bf16_f32 v32, v36, v37
	v_cvt_pk_bf16_f32 v33, v38, v39
	v_cvt_pk_bf16_f32 v34, v52, v53
	v_cvt_pk_bf16_f32 v35, v54, v55
	global_store_dwordx4 v[48:49], v[32:35], off offset:256
	s_nop 1
	s_nop 0
	v_lshl_add_u64 v[32:33], v[146:147], 0, s[18:19]
	v_mov_b32_e32 v34, v237
	v_fmamk_f32 v34, v34, 0x3a000000, v159
	v_mul_f32_e32 v35, 0x4b800000, v34
	v_cmp_gt_f32_e32 vcc, s56, v34
	s_nop 1
	v_cndmask_b32_e32 v34, v34, v35, vcc
	v_rsq_f32_e32 v36, v34
	v_add_co_u32_e64 v34, s[2:3], s59, v146
	v_mul_f32_e32 v37, 0x45800000, v36
	v_cndmask_b32_e32 v36, v36, v37, vcc
	v_pk_mul_f32 v[30:31], v[30:31], v[36:37] op_sel_hi:[1,0]
	v_pk_mul_f32 v[28:29], v[28:29], v[36:37] op_sel_hi:[1,0]
	v_pk_mul_f32 v[26:27], v[26:27], v[36:37] op_sel_hi:[1,0]
	v_pk_mul_f32 v[24:25], v[24:25], v[36:37] op_sel_hi:[1,0]
	v_pk_mul_f32 v[18:19], v[18:19], v[36:37] op_sel_hi:[1,0]
	v_pk_mul_f32 v[16:17], v[16:17], v[36:37] op_sel_hi:[1,0]
	v_pk_mul_f32 v[22:23], v[22:23], v[36:37] op_sel_hi:[1,0]
	v_pk_mul_f32 v[20:21], v[20:21], v[36:37] op_sel_hi:[1,0]
	v_max_f32_e32 v28, 0, v28
	v_max_f32_e32 v24, 0, v24
	v_max_f32_e32 v29, 0, v29
	v_max_f32_e32 v25, 0, v25
	v_max_f32_e32 v30, 0, v30
	v_max_f32_e32 v26, 0, v26
	v_max_f32_e32 v31, 0, v31
	v_max_f32_e32 v27, 0, v27
	v_max_f32_e32 v16, 0, v16
	v_max_f32_e32 v17, 0, v17
	v_max_f32_e32 v18, 0, v18
	v_max_f32_e32 v19, 0, v19
	v_addc_co_u32_e64 v35, s[2:3], 0, v147, s[2:3]
	v_max_f32_e32 v20, 0, v20
	v_max_f32_e32 v21, 0, v21
	v_max_f32_e32 v22, 0, v22
	v_max_f32_e32 v23, 0, v23
	v_mul_f32_e32 v28, v28, v28
	v_mul_f32_e32 v24, v24, v24
	v_mul_f32_e32 v29, v29, v29
	v_mul_f32_e32 v25, v25, v25
	v_mul_f32_e32 v30, v30, v30
	v_mul_f32_e32 v26, v26, v26
	v_mul_f32_e32 v31, v31, v31
	v_mul_f32_e32 v27, v27, v27
	v_mul_f32_e32 v36, v16, v16
	v_mul_f32_e32 v37, v17, v17
	v_mul_f32_e32 v38, v18, v18
	v_mul_f32_e32 v39, v19, v19
	v_cvt_pk_bf16_f32 v16, v28, v29
	v_cvt_pk_bf16_f32 v17, v30, v31
	v_cvt_pk_bf16_f32 v18, v24, v25
	v_cvt_pk_bf16_f32 v19, v26, v27
	v_mul_f32_e32 v20, v20, v20
	v_mul_f32_e32 v21, v21, v21
	v_mul_f32_e32 v22, v22, v22
	v_mul_f32_e32 v23, v23, v23
	global_store_dwordx4 v[34:35], v[16:19], off
	s_andn2_b64 vcc, exec, s[0:1]
	s_nop 0
	v_cvt_pk_bf16_f32 v16, v20, v21
	v_cvt_pk_bf16_f32 v17, v22, v23
	v_cvt_pk_bf16_f32 v18, v36, v37
	v_cvt_pk_bf16_f32 v19, v38, v39
	global_store_dwordx4 v[32:33], v[16:19], off offset:256
	s_nop 1
	s_nop 0
	v_lshl_add_u64 v[16:17], v[146:147], 0, s[20:21]
	v_mov_b32_e32 v18, v238
	v_fmamk_f32 v18, v18, 0x3a000000, v159
	v_mul_f32_e32 v19, 0x4b800000, v18
	v_cmp_gt_f32_e64 s[0:1], s56, v18
	s_nop 1
	v_cndmask_b32_e64 v18, v18, v19, s[0:1]
	v_rsq_f32_e32 v20, v18
	v_add_co_u32_e64 v18, s[2:3], s60, v146
	v_mul_f32_e32 v21, 0x45800000, v20
	v_cndmask_b32_e64 v20, v20, v21, s[0:1]
	v_pk_mul_f32 v[14:15], v[14:15], v[20:21] op_sel_hi:[1,0]
	v_pk_mul_f32 v[12:13], v[12:13], v[20:21] op_sel_hi:[1,0]
	v_pk_mul_f32 v[10:11], v[10:11], v[20:21] op_sel_hi:[1,0]
	v_pk_mul_f32 v[8:9], v[8:9], v[20:21] op_sel_hi:[1,0]
	v_pk_mul_f32 v[2:3], v[2:3], v[20:21] op_sel_hi:[1,0]
	v_pk_mul_f32 v[0:1], v[0:1], v[20:21] op_sel_hi:[1,0]
	v_pk_mul_f32 v[6:7], v[6:7], v[20:21] op_sel_hi:[1,0]
	v_pk_mul_f32 v[4:5], v[4:5], v[20:21] op_sel_hi:[1,0]
	v_max_f32_e32 v12, 0, v12
	v_max_f32_e32 v8, 0, v8
	v_max_f32_e32 v13, 0, v13
	v_max_f32_e32 v9, 0, v9
	v_max_f32_e32 v14, 0, v14
	v_max_f32_e32 v10, 0, v10
	v_max_f32_e32 v15, 0, v15
	v_max_f32_e32 v11, 0, v11
	v_max_f32_e32 v0, 0, v0
	v_max_f32_e32 v1, 0, v1
	v_max_f32_e32 v2, 0, v2
	v_max_f32_e32 v3, 0, v3
	v_addc_co_u32_e64 v19, s[2:3], 0, v147, s[2:3]
	v_max_f32_e32 v4, 0, v4
	v_max_f32_e32 v5, 0, v5
	v_max_f32_e32 v6, 0, v6
	v_max_f32_e32 v7, 0, v7
	v_mul_f32_e32 v12, v12, v12
	v_mul_f32_e32 v8, v8, v8
	v_mul_f32_e32 v13, v13, v13
	v_mul_f32_e32 v9, v9, v9
	v_mul_f32_e32 v14, v14, v14
	v_mul_f32_e32 v10, v10, v10
	v_mul_f32_e32 v15, v15, v15
	v_mul_f32_e32 v11, v11, v11
	v_mul_f32_e32 v20, v0, v0
	v_mul_f32_e32 v21, v1, v1
	v_mul_f32_e32 v22, v2, v2
	v_mul_f32_e32 v23, v3, v3
	v_cvt_pk_bf16_f32 v0, v12, v13
	v_cvt_pk_bf16_f32 v1, v14, v15
	v_cvt_pk_bf16_f32 v2, v8, v9
	v_cvt_pk_bf16_f32 v3, v10, v11
	s_mov_b64 s[0:1], -1
	v_mul_f32_e32 v4, v4, v4
	v_mul_f32_e32 v5, v5, v5
	v_mul_f32_e32 v6, v6, v6
	v_mul_f32_e32 v7, v7, v7
	global_store_dwordx4 v[18:19], v[0:3], off
	s_nop 1
	v_cvt_pk_bf16_f32 v0, v4, v5
	v_cvt_pk_bf16_f32 v1, v6, v7
	v_cvt_pk_bf16_f32 v2, v20, v21
	v_cvt_pk_bf16_f32 v3, v22, v23
	global_store_dwordx4 v[16:17], v[0:3], off offset:256
	s_cbranch_vccnz .LBB0_1418
	s_andn2_b64 vcc, exec, s[4:5]
	s_cbranch_vccnz .LBB0_1417
	s_barrier
	s_branch .LBB0_1417
